# GEMM phases: per-tile accumulator zeroing with 63 v_mov_b64 + 1 v_mov_b32 instead of 127 v_mov_b32
# baseline (speedup 1.0000x reference)
;   DI bool next(int i, Unit& u) const { const int pm = c + (i >> 2) * G; if (pm >= MTOK / 256) return false; u.pm = pm; u.pn = i & 3; return true; }
;   DI bool next(int i, Unit& u) const { if (i > 0 || c >= 32) return false; u.pm = c; u.pn = c >> 4; return true; }
; template <class Epi, class Sched, bool ALIGN_EPI = false, bool SP2 = false>
; __device__ __forceinline__ void gemm_phase(PG8_LAS unsigned char* lds, const Gemm g, const Sched& S, const Epi& E) {
;     ...
;         const bool has_next = S.next(ui + 1, nxt);
;         const char* nA = has_next ? (const char*)g.A + (size_t)nxt.pm * tstep : cA; const char* nB = has_next ? (const char*)g.Bt + (size_t)nxt.pn * tstep : cB;
;     ...
; #pragma unroll
;         for (int a = 0; a < 2; ++a)
; #pragma unroll
;             for (int b = 0; b < 2; ++b)
; #pragma unroll
;                 for (int m = 0; m < 4; ++m)
; #pragma unroll
;                     for (int n = 0; n < 2; ++n) acc[a][b][m][n] = (f32x4){0.f, 0.f, 0.f, 0.f};
.LBB0_451:
	s_ashr_i32 s15, s14, 31
	s_lshl_b64 s[16:17], s[14:15], 19
	s_add_u32 s16, s72, s16
	s_addc_u32 s17, s73, s17
	s_and_b64 s[18:19], s[6:7], exec
	s_cselect_b32 s15, s17, s21
	s_cselect_b32 s41, s16, s20
	s_ashr_i32 s13, s12, 31
	s_lshl_b64 s[18:19], s[12:13], 19
	s_add_u32 s18, s2, s18
	s_addc_u32 s19, s3, s19
	s_and_b64 s[24:25], s[6:7], exec
	s_cselect_b32 s13, s19, s23
	s_cselect_b32 s42, s18, s22
	s_add_u32 s20, s20, 0x40080
	s_addc_u32 s21, s21, 0
	s_add_u32 s43, s22, 0x100
	v_mov_b32_e32 v0, 0
	s_addc_u32 s44, s23, 0
	s_mov_b32 s45, -2
	v_mov_b32_e32 v1, v0
	v_mov_b64_e32 v[2:3], v[0:1]
	v_mov_b64_e32 v[4:5], v[0:1]
	v_mov_b64_e32 v[6:7], v[0:1]
	v_mov_b64_e32 v[8:9], v[0:1]
	v_mov_b64_e32 v[10:11], v[0:1]
	v_mov_b64_e32 v[12:13], v[0:1]
	v_mov_b64_e32 v[14:15], v[0:1]
	v_mov_b64_e32 v[16:17], v[0:1]
	v_mov_b64_e32 v[18:19], v[0:1]
	v_mov_b64_e32 v[20:21], v[0:1]
	v_mov_b64_e32 v[22:23], v[0:1]
	v_mov_b64_e32 v[24:25], v[0:1]
	v_mov_b64_e32 v[26:27], v[0:1]
	v_mov_b64_e32 v[28:29], v[0:1]
	v_mov_b64_e32 v[30:31], v[0:1]
	v_mov_b64_e32 v[32:33], v[0:1]
	v_mov_b64_e32 v[34:35], v[0:1]
	v_mov_b64_e32 v[36:37], v[0:1]
	v_mov_b64_e32 v[38:39], v[0:1]
	v_mov_b64_e32 v[40:41], v[0:1]
	v_mov_b64_e32 v[42:43], v[0:1]
	v_mov_b64_e32 v[44:45], v[0:1]
	v_mov_b64_e32 v[46:47], v[0:1]
	v_mov_b64_e32 v[48:49], v[0:1]
	v_mov_b64_e32 v[50:51], v[0:1]
	v_mov_b64_e32 v[52:53], v[0:1]
	v_mov_b64_e32 v[54:55], v[0:1]
	v_mov_b64_e32 v[56:57], v[0:1]
	v_mov_b64_e32 v[58:59], v[0:1]
	v_mov_b64_e32 v[60:61], v[0:1]
	v_mov_b64_e32 v[62:63], v[0:1]
	v_mov_b64_e32 v[64:65], v[0:1]
	v_mov_b64_e32 v[66:67], v[0:1]
	v_mov_b64_e32 v[68:69], v[0:1]
	v_mov_b64_e32 v[70:71], v[0:1]
	v_mov_b64_e32 v[72:73], v[0:1]
	v_mov_b64_e32 v[74:75], v[0:1]
	v_mov_b64_e32 v[76:77], v[0:1]
	v_mov_b64_e32 v[78:79], v[0:1]
	v_mov_b64_e32 v[80:81], v[0:1]
	v_mov_b64_e32 v[82:83], v[0:1]
	v_mov_b64_e32 v[84:85], v[0:1]
	v_mov_b64_e32 v[86:87], v[0:1]
	v_mov_b64_e32 v[88:89], v[0:1]
	v_mov_b64_e32 v[90:91], v[0:1]
	v_mov_b64_e32 v[92:93], v[0:1]
	v_mov_b64_e32 v[94:95], v[0:1]
	v_mov_b64_e32 v[96:97], v[0:1]
	v_mov_b64_e32 v[98:99], v[0:1]
	v_mov_b64_e32 v[100:101], v[0:1]
	v_mov_b64_e32 v[102:103], v[0:1]
	v_mov_b64_e32 v[104:105], v[0:1]
	v_mov_b64_e32 v[106:107], v[0:1]
	v_mov_b64_e32 v[108:109], v[0:1]
	v_mov_b64_e32 v[110:111], v[0:1]
	v_mov_b64_e32 v[112:113], v[0:1]
	v_mov_b64_e32 v[114:115], v[0:1]
	v_mov_b64_e32 v[116:117], v[0:1]
	v_mov_b64_e32 v[118:119], v[0:1]
	v_mov_b64_e32 v[120:121], v[0:1]
	v_mov_b64_e32 v[122:123], v[0:1]
	v_mov_b64_e32 v[124:125], v[0:1]
	v_mov_b64_e32 v[126:127], v[0:1]

; template <class Epi, class Sched, bool ALIGN_EPI = false, bool SP2 = false>
; __device__ __forceinline__ void gemm_phase(PG8_LAS unsigned char* lds, const Gemm g, const Sched& S, const Epi& E) {
;     ...
; #pragma unroll
;         for (int a = 0; a < 2; ++a)
; #pragma unroll
;             for (int b = 0; b < 2; ++b)
; #pragma unroll
;                 for (int m = 0; m < 4; ++m)
; #pragma unroll
;                     for (int n = 0; n < 2; ++n) acc[a][b][m][n] = (f32x4){0.f, 0.f, 0.f, 0.f};
.LBB0_534:
	s_add_u32 s40, s20, 0x100
	v_mov_b32_e32 v0, 0
	s_addc_u32 s41, s21, 0
	s_mov_b32 s42, -2
	s_waitcnt lgkmcnt(0)
	v_mov_b32_e32 v1, v0
	v_mov_b64_e32 v[2:3], v[0:1]
	v_mov_b64_e32 v[4:5], v[0:1]
	v_mov_b64_e32 v[6:7], v[0:1]
	v_mov_b64_e32 v[8:9], v[0:1]
	v_mov_b64_e32 v[10:11], v[0:1]
	v_mov_b64_e32 v[12:13], v[0:1]
	v_mov_b64_e32 v[14:15], v[0:1]
	v_mov_b64_e32 v[16:17], v[0:1]
	v_mov_b64_e32 v[18:19], v[0:1]
	v_mov_b64_e32 v[20:21], v[0:1]
	v_mov_b64_e32 v[22:23], v[0:1]
	v_mov_b64_e32 v[24:25], v[0:1]
	v_mov_b64_e32 v[26:27], v[0:1]
	v_mov_b64_e32 v[28:29], v[0:1]
	v_mov_b64_e32 v[30:31], v[0:1]
	v_mov_b64_e32 v[32:33], v[0:1]
	v_mov_b64_e32 v[34:35], v[0:1]
	v_mov_b64_e32 v[36:37], v[0:1]
	v_mov_b64_e32 v[38:39], v[0:1]
	v_mov_b64_e32 v[40:41], v[0:1]
	v_mov_b64_e32 v[42:43], v[0:1]
	v_mov_b64_e32 v[44:45], v[0:1]
	v_mov_b64_e32 v[46:47], v[0:1]
	v_mov_b64_e32 v[48:49], v[0:1]
	v_mov_b64_e32 v[50:51], v[0:1]
	v_mov_b64_e32 v[52:53], v[0:1]
	v_mov_b64_e32 v[54:55], v[0:1]
	v_mov_b64_e32 v[56:57], v[0:1]
	v_mov_b64_e32 v[58:59], v[0:1]
	v_mov_b64_e32 v[60:61], v[0:1]
	v_mov_b64_e32 v[62:63], v[0:1]
	v_mov_b64_e32 v[64:65], v[0:1]
	v_mov_b64_e32 v[66:67], v[0:1]
	v_mov_b64_e32 v[68:69], v[0:1]
	v_mov_b64_e32 v[70:71], v[0:1]
	v_mov_b64_e32 v[72:73], v[0:1]
	v_mov_b64_e32 v[74:75], v[0:1]
	v_mov_b64_e32 v[76:77], v[0:1]
	v_mov_b64_e32 v[78:79], v[0:1]
	v_mov_b64_e32 v[80:81], v[0:1]
	v_mov_b64_e32 v[82:83], v[0:1]
	v_mov_b64_e32 v[84:85], v[0:1]
	v_mov_b64_e32 v[86:87], v[0:1]
	v_mov_b64_e32 v[88:89], v[0:1]
	v_mov_b64_e32 v[90:91], v[0:1]
	v_mov_b64_e32 v[92:93], v[0:1]
	v_mov_b64_e32 v[94:95], v[0:1]
	v_mov_b64_e32 v[96:97], v[0:1]
	v_mov_b64_e32 v[98:99], v[0:1]
	v_mov_b64_e32 v[100:101], v[0:1]
	v_mov_b64_e32 v[102:103], v[0:1]
	v_mov_b64_e32 v[104:105], v[0:1]
	v_mov_b64_e32 v[106:107], v[0:1]
	v_mov_b64_e32 v[108:109], v[0:1]
	v_mov_b64_e32 v[110:111], v[0:1]
	v_mov_b64_e32 v[112:113], v[0:1]
	v_mov_b64_e32 v[114:115], v[0:1]
	v_mov_b64_e32 v[116:117], v[0:1]
	v_mov_b64_e32 v[118:119], v[0:1]
	v_mov_b64_e32 v[120:121], v[0:1]
	v_mov_b64_e32 v[122:123], v[0:1]
	v_mov_b64_e32 v[124:125], v[0:1]
	v_mov_b64_e32 v[126:127], v[0:1]

;   DI bool next(int i, Unit& u) const { const int pm = c + (i >> 2) * G; if (pm >= MTOK / 256) return false; u.pm = pm; u.pn = i & 3; return true; }
;   DI bool next(int i, Unit& u) const { if (i > 0 || c >= 32) return false; u.pm = c; u.pn = c >> 4; return true; }
; template <class Epi, class Sched, bool ALIGN_EPI = false, bool SP2 = false>
; __device__ __forceinline__ void gemm_phase(PG8_LAS unsigned char* lds, const Gemm g, const Sched& S, const Epi& E) {
;     ...
;         const bool has_next = S.next(ui + 1, nxt);
;         const char* nA = has_next ? (const char*)g.A + (size_t)nxt.pm * tstep : cA; const char* nB = has_next ? (const char*)g.Bt + (size_t)nxt.pn * tstep : cB;
;     ...
; #pragma unroll
;         for (int a = 0; a < 2; ++a)
; #pragma unroll
;             for (int b = 0; b < 2; ++b)
; #pragma unroll
;                 for (int m = 0; m < 4; ++m)
; #pragma unroll
;                     for (int n = 0; n < 2; ++n) acc[a][b][m][n] = (f32x4){0.f, 0.f, 0.f, 0.f};
.LBB0_623:
	s_ashr_i32 s27, s26, 31
	s_lshl_b64 s[14:15], s[26:27], 19
	s_add_u32 s28, s43, s14
	s_addc_u32 s29, s44, s15
	s_and_b64 s[14:15], s[8:9], exec
	s_cselect_b32 s6, s29, s11
	s_cselect_b32 s27, s28, s10
	s_ashr_i32 s25, s24, 31
	s_lshl_b64 s[14:15], s[24:25], 19
	v_readlane_b32 s2, v253, 45
	s_add_u32 s30, s2, s14
	v_readlane_b32 s2, v253, 46
	s_addc_u32 s31, s2, s15
	s_and_b64 s[14:15], s[8:9], exec
	s_cselect_b32 s25, s31, s13
	s_cselect_b32 s34, s30, s12
	s_add_u32 s10, s10, 0x40080
	s_addc_u32 s11, s11, 0
	s_add_u32 s35, s12, 0x100
	v_mov_b32_e32 v0, 0
	s_addc_u32 s36, s13, 0
	s_mov_b32 s37, -2
	v_mov_b32_e32 v1, v0
	v_mov_b64_e32 v[2:3], v[0:1]
	v_mov_b64_e32 v[4:5], v[0:1]
	v_mov_b64_e32 v[6:7], v[0:1]
	v_mov_b64_e32 v[8:9], v[0:1]
	v_mov_b64_e32 v[10:11], v[0:1]
	v_mov_b64_e32 v[12:13], v[0:1]
	v_mov_b64_e32 v[14:15], v[0:1]
	v_mov_b64_e32 v[16:17], v[0:1]
	v_mov_b64_e32 v[18:19], v[0:1]
	v_mov_b64_e32 v[20:21], v[0:1]
	v_mov_b64_e32 v[22:23], v[0:1]
	v_mov_b64_e32 v[24:25], v[0:1]
	v_mov_b64_e32 v[26:27], v[0:1]
	v_mov_b64_e32 v[28:29], v[0:1]
	v_mov_b64_e32 v[30:31], v[0:1]
	v_mov_b64_e32 v[32:33], v[0:1]
	v_mov_b64_e32 v[34:35], v[0:1]
	v_mov_b64_e32 v[36:37], v[0:1]
	v_mov_b64_e32 v[38:39], v[0:1]
	v_mov_b64_e32 v[40:41], v[0:1]
	v_mov_b64_e32 v[42:43], v[0:1]
	v_mov_b64_e32 v[44:45], v[0:1]
	v_mov_b64_e32 v[46:47], v[0:1]
	v_mov_b64_e32 v[48:49], v[0:1]
	v_mov_b64_e32 v[50:51], v[0:1]
	v_mov_b64_e32 v[52:53], v[0:1]
	v_mov_b64_e32 v[54:55], v[0:1]
	v_mov_b64_e32 v[56:57], v[0:1]
	v_mov_b64_e32 v[58:59], v[0:1]
	v_mov_b64_e32 v[60:61], v[0:1]
	v_mov_b64_e32 v[62:63], v[0:1]
	v_mov_b64_e32 v[64:65], v[0:1]
	v_mov_b64_e32 v[66:67], v[0:1]
	v_mov_b64_e32 v[68:69], v[0:1]
	v_mov_b64_e32 v[70:71], v[0:1]
	v_mov_b64_e32 v[72:73], v[0:1]
	v_mov_b64_e32 v[74:75], v[0:1]
	v_mov_b64_e32 v[76:77], v[0:1]
	v_mov_b64_e32 v[78:79], v[0:1]
	v_mov_b64_e32 v[80:81], v[0:1]
	v_mov_b64_e32 v[82:83], v[0:1]
	v_mov_b64_e32 v[84:85], v[0:1]
	v_mov_b64_e32 v[86:87], v[0:1]
	v_mov_b64_e32 v[88:89], v[0:1]
	v_mov_b64_e32 v[90:91], v[0:1]
	v_mov_b64_e32 v[92:93], v[0:1]
	v_mov_b64_e32 v[94:95], v[0:1]
	v_mov_b64_e32 v[96:97], v[0:1]
	v_mov_b64_e32 v[98:99], v[0:1]
	v_mov_b64_e32 v[100:101], v[0:1]
	v_mov_b64_e32 v[102:103], v[0:1]
	v_mov_b64_e32 v[104:105], v[0:1]
	v_mov_b64_e32 v[106:107], v[0:1]
	v_mov_b64_e32 v[108:109], v[0:1]
	v_mov_b64_e32 v[110:111], v[0:1]
	v_mov_b64_e32 v[112:113], v[0:1]
	v_mov_b64_e32 v[114:115], v[0:1]
	v_mov_b64_e32 v[116:117], v[0:1]
	v_mov_b64_e32 v[118:119], v[0:1]
	v_mov_b64_e32 v[120:121], v[0:1]
	v_mov_b64_e32 v[122:123], v[0:1]
	v_mov_b64_e32 v[124:125], v[0:1]
	v_mov_b64_e32 v[126:127], v[0:1]

; #define PG8_STAGE(bufoff, gbase, voff) do { _Pragma("unroll") for (int _i = 0; _i < 2; ++_i) \
;         __builtin_amdgcn_global_load_lds((const unsigned*)((const char*)(gbase) + (voff)[_i]), (PG8_LAS unsigned*)(lds + (bufoff) + ldsw + _i * 8192), 16, 0, 0); } while (0)
; #define PG8_WAIT_V(n) asm volatile("s_waitcnt vmcnt(" #n ")" ::: "memory")
; #define PG8_BAR __builtin_amdgcn_s_barrier()
; template <class Epi, class Sched, bool ALIGN_EPI = false, bool SP2 = false>
; __device__ __forceinline__ void gemm_phase(PG8_LAS unsigned char* lds, const Gemm g, const Sched& S, const Epi& E) {
;     ...
;     for (int i = 0; i < 2; ++i) { int R, C; stage_rc(tid * 16 + i * 8192, R, C); const int Rb = Epi::PERM ? ((R & ~31) + perm32(R & 31)) : R;
;         voffA[i] = (unsigned)(R * K + C) * 2u; voffB[i] = (unsigned)(Rb * K + C) * 2u; }
;     const size_t kstep = (size_t)(BK * 2);
;     const size_t hstep = (size_t)HALF * K * 2;
;     const size_t tstep = 2 * hstep;
;     const unsigned ldsw = (unsigned)wid * 1024u;
;     const int aoff = lds_byte(wr * 64 + fr, fq * 8), boff = lds_byte(wc * 32 + fr, fq * 8);
;     ...
;     f32x4 acc[2][2][4][2];
; #pragma unroll
;     for (int a = 0; a < 2; ++a)
; #pragma unroll
;         for (int b = 0; b < 2; ++b)
; #pragma unroll
;             for (int m = 0; m < 4; ++m)
; #pragma unroll
;                 for (int n = 0; n < 2; ++n) acc[a][b][m][n] = (f32x4){0.f, 0.f, 0.f, 0.f};
;     bf16x8 At[4][2], B0[2][2], B1[2][2];
;     const char* cA = (const char*)g.A + (size_t)cur.pm * tstep; const char* cB = (const char*)g.Bt + (size_t)cur.pn * tstep;
;     S.a_ready(cur);
;     if constexpr (SP2) {
;         PG8_STAGE(PG8_SB(0, 0), cB, voffB); PG8_STAGE(PG8_SB(0, 1), cB + hstep, voffB); PG8_STAGE(PG8_SA(0, 0), cA, voffA); PG8_STAGE(PG8_SA(0, 1), cA + hstep, voffA);
;         if (wr == 1) PG8_BAR;
;         PG8_WAIT_V(2); PG8_BAR;
;         PG8_STAGE(PG8_SB(1, 0), cB + kstep, voffB); PG8_STAGE(PG8_SA(1, 0), cA + kstep, voffA); PG8_STAGE(PG8_SB(1, 1), cB + hstep + kstep, voffB);
;         PG8_WAIT_V(6); PG8_BAR;
.LBB0_821:
	v_lshrrev_b32_e32 v16, 1, v3
	v_lshl_add_u64 v[8:9], s[68:69], 0, v[186:187]
	v_mov_b32_e32 v129, v187
	v_and_b32_e32 v139, 24, v16
	s_lshl_b32 s10, s10, 5
	v_lshl_add_u64 v[10:11], s[68:69], 0, v[128:129]
	v_mov_b32_e32 v133, v187
	v_and_b32_e32 v7, 15, v3
	v_lshlrev_b32_e32 v16, 1, v139
	v_lshlrev_b32_e32 v3, 2, v3
	s_and_b32 s18, s10, 0x60
	s_add_i32 m0, s3, 0x18000
	v_lshl_add_u64 v[8:9], v[8:9], 0, s[92:93]
	v_lshl_add_u64 v[12:13], s[70:71], 0, v[132:133]
	v_mov_b32_e32 v131, v187
	v_lshl_or_b32 v138, s11, 6, v7
	v_lshl_or_b32 v7, v7, 6, v16
	s_lshl_b32 s11, s11, 13
	v_and_b32_e32 v3, 32, v3
	s_lshl_b32 s10, s18, 7
	s_waitcnt vmcnt(2)
	s_barrier
	global_load_lds_dwordx4 v[8:9], off
	v_lshl_add_u64 v[8:9], v[10:11], 0, s[92:93]
	s_add_i32 m0, s3, 0x1a000
	s_add_i32 s19, s3, 0x8000
	v_lshl_add_u64 v[14:15], s[70:71], 0, v[130:131]
	v_bitop3_b32 v16, v7, s11, v3 bitop3:0xde
	v_bitop3_b32 v140, v7, s10, v3 bitop3:0xde
	global_load_lds_dwordx4 v[8:9], off
	v_lshl_add_u64 v[8:9], v[12:13], 0, s[92:93]
	s_mov_b32 m0, s19
	s_add_i32 s20, s3, 0xa000
	v_readlane_b32 s10, v254, 31
	global_load_lds_dwordx4 v[8:9], off
	v_lshl_add_u64 v[8:9], v[14:15], 0, s[92:93]
	s_mov_b32 m0, s20
	v_readlane_b32 s11, v254, 32
	global_load_lds_dwordx4 v[8:9], off
	s_add_i32 m0, s3, 0x1c000
	v_lshl_add_u64 v[8:9], s[10:11], 0, v[186:187]
	global_load_lds_dwordx4 v[8:9], off
	v_lshl_add_u64 v[8:9], s[10:11], 0, v[128:129]
	s_add_i32 m0, s3, 0x1e000
	v_lshlrev_b32_e32 v3, 15, v5
	global_load_lds_dwordx4 v[8:9], off
	v_and_b32_e32 v3, 0xffff0000, v3
	v_lshl_add_u32 v3, v4, 12, v3
	v_and_b32_e32 v4, 1, v5
	v_lshl_or_b32 v3, v4, 6, v3
	v_lshl_add_u32 v4, v6, 1, v3
	v_lshlrev_b32_e32 v3, 15, v0
	v_and_b32_e32 v3, 0xffff0000, v3
	v_lshl_add_u32 v1, v1, 12, v3
	v_and_b32_e32 v0, 1, v0
	v_readlane_b32 s10, v255, 1
	v_lshl_or_b32 v0, v0, 6, v1
	s_waitcnt vmcnt(6)
	v_readlane_b32 s11, v255, 2
	v_lshl_add_u32 v0, v2, 1, v0
	v_mov_b32_e32 v1, v187
	v_mov_b32_e32 v5, v187
	v_lshl_add_u64 v[136:137], s[10:11], 0, v[0:1]
	v_mov_b32_e32 v0, 0
	v_lshl_add_u64 v[134:135], s[10:11], 0, v[4:5]
	s_mov_b32 s21, -2
	s_mov_b64 s[10:11], 0
	v_add_u32_e32 v141, 0, v16
	v_mov_b32_e32 v1, v0
	v_mov_b64_e32 v[2:3], v[0:1]
	v_mov_b64_e32 v[4:5], v[0:1]
	v_mov_b64_e32 v[6:7], v[0:1]
	v_mov_b64_e32 v[8:9], v[0:1]
	v_mov_b64_e32 v[10:11], v[0:1]
	v_mov_b64_e32 v[12:13], v[0:1]
	v_mov_b64_e32 v[14:15], v[0:1]
	v_mov_b64_e32 v[16:17], v[0:1]
	v_mov_b64_e32 v[18:19], v[0:1]
	v_mov_b64_e32 v[20:21], v[0:1]
	v_mov_b64_e32 v[22:23], v[0:1]
	v_mov_b64_e32 v[24:25], v[0:1]
	v_mov_b64_e32 v[26:27], v[0:1]
	v_mov_b64_e32 v[28:29], v[0:1]
	v_mov_b64_e32 v[30:31], v[0:1]
	v_mov_b64_e32 v[32:33], v[0:1]
	v_mov_b64_e32 v[34:35], v[0:1]
	v_mov_b64_e32 v[36:37], v[0:1]
	v_mov_b64_e32 v[38:39], v[0:1]
	v_mov_b64_e32 v[40:41], v[0:1]
	v_mov_b64_e32 v[42:43], v[0:1]
	v_mov_b64_e32 v[44:45], v[0:1]
	v_mov_b64_e32 v[46:47], v[0:1]
	v_mov_b64_e32 v[48:49], v[0:1]
	v_mov_b64_e32 v[50:51], v[0:1]
	v_mov_b64_e32 v[52:53], v[0:1]
	v_mov_b64_e32 v[54:55], v[0:1]
	v_mov_b64_e32 v[56:57], v[0:1]
	v_mov_b64_e32 v[58:59], v[0:1]
	v_mov_b64_e32 v[60:61], v[0:1]
	v_mov_b64_e32 v[62:63], v[0:1]
	v_mov_b64_e32 v[64:65], v[0:1]
	v_mov_b64_e32 v[66:67], v[0:1]
	v_mov_b64_e32 v[68:69], v[0:1]
	v_mov_b64_e32 v[70:71], v[0:1]
	v_mov_b64_e32 v[72:73], v[0:1]
	v_mov_b64_e32 v[74:75], v[0:1]
	v_mov_b64_e32 v[76:77], v[0:1]
	v_mov_b64_e32 v[78:79], v[0:1]
	v_mov_b64_e32 v[80:81], v[0:1]
	v_mov_b64_e32 v[82:83], v[0:1]
	v_mov_b64_e32 v[84:85], v[0:1]
	v_mov_b64_e32 v[86:87], v[0:1]
	v_mov_b64_e32 v[88:89], v[0:1]
	v_mov_b64_e32 v[90:91], v[0:1]
	v_mov_b64_e32 v[92:93], v[0:1]
	v_mov_b64_e32 v[94:95], v[0:1]
	v_mov_b64_e32 v[96:97], v[0:1]
	v_mov_b64_e32 v[98:99], v[0:1]
	v_mov_b64_e32 v[100:101], v[0:1]
	v_mov_b64_e32 v[102:103], v[0:1]
	v_mov_b64_e32 v[104:105], v[0:1]
	v_mov_b64_e32 v[106:107], v[0:1]
	v_mov_b64_e32 v[108:109], v[0:1]
	v_mov_b64_e32 v[110:111], v[0:1]
	v_mov_b64_e32 v[112:113], v[0:1]
	v_mov_b64_e32 v[114:115], v[0:1]
	v_mov_b64_e32 v[116:117], v[0:1]
	v_mov_b64_e32 v[118:119], v[0:1]
	v_mov_b64_e32 v[120:121], v[0:1]
	v_mov_b64_e32 v[122:123], v[0:1]
	v_mov_b64_e32 v[124:125], v[0:1]
	v_mov_b64_e32 v[126:127], v[0:1]
	s_barrier

;   DI bool next(int i, Unit& u) const { const int pm = c + (i >> 2) * G; if (pm >= MTOK / 256) return false; u.pm = pm; u.pn = i & 3; return true; }
;   DI bool next(int i, Unit& u) const { if (i > 0 || c >= 32) return false; u.pm = c; u.pn = c >> 4; return true; }
; template <class Epi, class Sched, bool ALIGN_EPI = false, bool SP2 = false>
; __device__ __forceinline__ void gemm_phase(PG8_LAS unsigned char* lds, const Gemm g, const Sched& S, const Epi& E) {
;     ...
;         const bool has_next = S.next(ui + 1, nxt);
;         const char* nA = has_next ? (const char*)g.A + (size_t)nxt.pm * tstep : cA; const char* nB = has_next ? (const char*)g.Bt + (size_t)nxt.pn * tstep : cB;
;     ...
; #pragma unroll
;         for (int a = 0; a < 2; ++a)
; #pragma unroll
;             for (int b = 0; b < 2; ++b)
; #pragma unroll
;                 for (int m = 0; m < 4; ++m)
; #pragma unroll
;                     for (int n = 0; n < 2; ++n) acc[a][b][m][n] = (f32x4){0.f, 0.f, 0.f, 0.f};
.LBB0_1077:
	s_ashr_i32 s19, s18, 31
	s_lshl_b64 s[20:21], s[18:19], 19
	v_readlane_b32 s2, v253, 17
	s_add_u32 s20, s2, s20
	v_readlane_b32 s2, v253, 18
	s_addc_u32 s21, s2, s21
	s_and_b64 s[22:23], s[10:11], exec
	s_cselect_b32 s19, s21, s25
	s_cselect_b32 s38, s20, s24
	s_ashr_i32 s17, s16, 31
	s_lshl_b64 s[22:23], s[16:17], 19
	v_readlane_b32 s2, v253, 13
	s_add_u32 s22, s2, s22
	v_readlane_b32 s2, v253, 14
	s_addc_u32 s23, s2, s23
	s_and_b64 s[28:29], s[10:11], exec
	s_cselect_b32 s17, s23, s27
	s_cselect_b32 s39, s22, s26
	s_add_u32 s24, s24, 0x40080
	s_addc_u32 s25, s25, 0
	s_add_u32 s40, s26, 0x100
	v_mov_b32_e32 v0, 0
	s_addc_u32 s41, s27, 0
	s_mov_b32 s42, -2
	v_mov_b32_e32 v1, v0
	v_mov_b64_e32 v[2:3], v[0:1]
	v_mov_b64_e32 v[4:5], v[0:1]
	v_mov_b64_e32 v[6:7], v[0:1]
	v_mov_b64_e32 v[8:9], v[0:1]
	v_mov_b64_e32 v[10:11], v[0:1]
	v_mov_b64_e32 v[12:13], v[0:1]
	v_mov_b64_e32 v[14:15], v[0:1]
	v_mov_b64_e32 v[16:17], v[0:1]
	v_mov_b64_e32 v[18:19], v[0:1]
	v_mov_b64_e32 v[20:21], v[0:1]
	v_mov_b64_e32 v[22:23], v[0:1]
	v_mov_b64_e32 v[24:25], v[0:1]
	v_mov_b64_e32 v[26:27], v[0:1]
	v_mov_b64_e32 v[28:29], v[0:1]
	v_mov_b64_e32 v[30:31], v[0:1]
	v_mov_b64_e32 v[32:33], v[0:1]
	v_mov_b64_e32 v[34:35], v[0:1]
	v_mov_b64_e32 v[36:37], v[0:1]
	v_mov_b64_e32 v[38:39], v[0:1]
	v_mov_b64_e32 v[40:41], v[0:1]
	v_mov_b64_e32 v[42:43], v[0:1]
	v_mov_b64_e32 v[44:45], v[0:1]
	v_mov_b64_e32 v[46:47], v[0:1]
	v_mov_b64_e32 v[48:49], v[0:1]
	v_mov_b64_e32 v[50:51], v[0:1]
	v_mov_b64_e32 v[52:53], v[0:1]
	v_mov_b64_e32 v[54:55], v[0:1]
	v_mov_b64_e32 v[56:57], v[0:1]
	v_mov_b64_e32 v[58:59], v[0:1]
	v_mov_b64_e32 v[60:61], v[0:1]
	v_mov_b64_e32 v[62:63], v[0:1]
	v_mov_b64_e32 v[64:65], v[0:1]
	v_mov_b64_e32 v[66:67], v[0:1]
	v_mov_b64_e32 v[68:69], v[0:1]
	v_mov_b64_e32 v[70:71], v[0:1]
	v_mov_b64_e32 v[72:73], v[0:1]
	v_mov_b64_e32 v[74:75], v[0:1]
	v_mov_b64_e32 v[76:77], v[0:1]
	v_mov_b64_e32 v[78:79], v[0:1]
	v_mov_b64_e32 v[80:81], v[0:1]
	v_mov_b64_e32 v[82:83], v[0:1]
	v_mov_b64_e32 v[84:85], v[0:1]
	v_mov_b64_e32 v[86:87], v[0:1]
	v_mov_b64_e32 v[88:89], v[0:1]
	v_mov_b64_e32 v[90:91], v[0:1]
	v_mov_b64_e32 v[92:93], v[0:1]
	v_mov_b64_e32 v[94:95], v[0:1]
	v_mov_b64_e32 v[96:97], v[0:1]
	v_mov_b64_e32 v[98:99], v[0:1]
	v_mov_b64_e32 v[100:101], v[0:1]
	v_mov_b64_e32 v[102:103], v[0:1]
	v_mov_b64_e32 v[104:105], v[0:1]
	v_mov_b64_e32 v[106:107], v[0:1]
	v_mov_b64_e32 v[108:109], v[0:1]
	v_mov_b64_e32 v[110:111], v[0:1]
	v_mov_b64_e32 v[112:113], v[0:1]
	v_mov_b64_e32 v[114:115], v[0:1]
	v_mov_b64_e32 v[116:117], v[0:1]
	v_mov_b64_e32 v[118:119], v[0:1]
	v_mov_b64_e32 v[120:121], v[0:1]
	v_mov_b64_e32 v[122:123], v[0:1]
	v_mov_b64_e32 v[124:125], v[0:1]
	v_mov_b64_e32 v[126:127], v[0:1]
	s_waitcnt vmcnt(0)

;   DI bool next(int i, Unit& u) const { const int pm = c + (i >> 2) * G; if (pm >= MTOK / 256) return false; u.pm = pm; u.pn = i & 3; return true; }
;   DI bool next(int i, Unit& u) const { if (i > 0 || c >= 32) return false; u.pm = c; u.pn = c >> 4; return true; }
; template <class Epi, class Sched, bool ALIGN_EPI = false, bool SP2 = false>
; __device__ __forceinline__ void gemm_phase(PG8_LAS unsigned char* lds, const Gemm g, const Sched& S, const Epi& E) {
;     ...
;         const bool has_next = S.next(ui + 1, nxt);
;         const char* nA = has_next ? (const char*)g.A + (size_t)nxt.pm * tstep : cA; const char* nB = has_next ? (const char*)g.Bt + (size_t)nxt.pn * tstep : cB;
;     ...
; #pragma unroll
;         for (int a = 0; a < 2; ++a)
; #pragma unroll
;             for (int b = 0; b < 2; ++b)
; #pragma unroll
;                 for (int m = 0; m < 4; ++m)
; #pragma unroll
;                     for (int n = 0; n < 2; ++n) acc[a][b][m][n] = (f32x4){0.f, 0.f, 0.f, 0.f};
.LBB0_1169:
	s_ashr_i32 s19, s18, 31
	s_lshl_b64 s[20:21], s[18:19], 19
	s_add_u32 s20, s80, s20
	s_addc_u32 s21, s81, s21
	s_and_b64 s[22:23], s[10:11], exec
	s_cselect_b32 s19, s21, s25
	s_cselect_b32 s38, s20, s24
	s_ashr_i32 s17, s16, 31
	s_lshl_b64 s[22:23], s[16:17], 19
	v_readlane_b32 s2, v253, 53
	s_add_u32 s22, s2, s22
	v_readlane_b32 s2, v253, 54
	s_addc_u32 s23, s2, s23
	s_and_b64 s[28:29], s[10:11], exec
	s_cselect_b32 s17, s23, s27
	s_cselect_b32 s39, s22, s26
	s_add_u32 s24, s24, 0x40080
	s_addc_u32 s25, s25, 0
	s_add_u32 s40, s26, 0x100
	v_mov_b32_e32 v0, 0
	s_addc_u32 s41, s27, 0
	s_mov_b32 s42, -2
	v_mov_b32_e32 v1, v0
	v_mov_b64_e32 v[2:3], v[0:1]
	v_mov_b64_e32 v[4:5], v[0:1]
	v_mov_b64_e32 v[6:7], v[0:1]
	v_mov_b64_e32 v[8:9], v[0:1]
	v_mov_b64_e32 v[10:11], v[0:1]
	v_mov_b64_e32 v[12:13], v[0:1]
	v_mov_b64_e32 v[14:15], v[0:1]
	v_mov_b64_e32 v[16:17], v[0:1]
	v_mov_b64_e32 v[18:19], v[0:1]
	v_mov_b64_e32 v[20:21], v[0:1]
	v_mov_b64_e32 v[22:23], v[0:1]
	v_mov_b64_e32 v[24:25], v[0:1]
	v_mov_b64_e32 v[26:27], v[0:1]
	v_mov_b64_e32 v[28:29], v[0:1]
	v_mov_b64_e32 v[30:31], v[0:1]
	v_mov_b64_e32 v[32:33], v[0:1]
	v_mov_b64_e32 v[34:35], v[0:1]
	v_mov_b64_e32 v[36:37], v[0:1]
	v_mov_b64_e32 v[38:39], v[0:1]
	v_mov_b64_e32 v[40:41], v[0:1]
	v_mov_b64_e32 v[42:43], v[0:1]
	v_mov_b64_e32 v[44:45], v[0:1]
	v_mov_b64_e32 v[46:47], v[0:1]
	v_mov_b64_e32 v[48:49], v[0:1]
	v_mov_b64_e32 v[50:51], v[0:1]
	v_mov_b64_e32 v[52:53], v[0:1]
	v_mov_b64_e32 v[54:55], v[0:1]
	v_mov_b64_e32 v[56:57], v[0:1]
	v_mov_b64_e32 v[58:59], v[0:1]
	v_mov_b64_e32 v[60:61], v[0:1]
	v_mov_b64_e32 v[62:63], v[0:1]
	v_mov_b64_e32 v[64:65], v[0:1]
	v_mov_b64_e32 v[66:67], v[0:1]
	v_mov_b64_e32 v[68:69], v[0:1]
	v_mov_b64_e32 v[70:71], v[0:1]
	v_mov_b64_e32 v[72:73], v[0:1]
	v_mov_b64_e32 v[74:75], v[0:1]
	v_mov_b64_e32 v[76:77], v[0:1]
	v_mov_b64_e32 v[78:79], v[0:1]
	v_mov_b64_e32 v[80:81], v[0:1]
	v_mov_b64_e32 v[82:83], v[0:1]
	v_mov_b64_e32 v[84:85], v[0:1]
	v_mov_b64_e32 v[86:87], v[0:1]
	v_mov_b64_e32 v[88:89], v[0:1]
	v_mov_b64_e32 v[90:91], v[0:1]
	v_mov_b64_e32 v[92:93], v[0:1]
	v_mov_b64_e32 v[94:95], v[0:1]
	v_mov_b64_e32 v[96:97], v[0:1]
	v_mov_b64_e32 v[98:99], v[0:1]
	v_mov_b64_e32 v[100:101], v[0:1]
	v_mov_b64_e32 v[102:103], v[0:1]
	v_mov_b64_e32 v[104:105], v[0:1]
	v_mov_b64_e32 v[106:107], v[0:1]
	v_mov_b64_e32 v[108:109], v[0:1]
	v_mov_b64_e32 v[110:111], v[0:1]
	v_mov_b64_e32 v[112:113], v[0:1]
	v_mov_b64_e32 v[114:115], v[0:1]
	v_mov_b64_e32 v[116:117], v[0:1]
	v_mov_b64_e32 v[118:119], v[0:1]
	v_mov_b64_e32 v[120:121], v[0:1]
	v_mov_b64_e32 v[122:123], v[0:1]
	v_mov_b64_e32 v[124:125], v[0:1]
	v_mov_b64_e32 v[126:127], v[0:1]
	s_waitcnt vmcnt(0)

;   DI bool next(int i, Unit& u) const { const int pm = c + (i >> 2) * G; if (pm >= MTOK / 256) return false; u.pm = pm; u.pn = i & 3; return true; }
;   DI bool next(int i, Unit& u) const { if (i > 0 || c >= 32) return false; u.pm = c; u.pn = c >> 4; return true; }
; template <class Epi, class Sched, bool ALIGN_EPI = false, bool SP2 = false>
; __device__ __forceinline__ void gemm_phase(PG8_LAS unsigned char* lds, const Gemm g, const Sched& S, const Epi& E) {
;     ...
;         const bool has_next = S.next(ui + 1, nxt);
;         const char* nA = has_next ? (const char*)g.A + (size_t)nxt.pm * tstep : cA; const char* nB = has_next ? (const char*)g.Bt + (size_t)nxt.pn * tstep : cB;
;     ...
; #pragma unroll
;         for (int a = 0; a < 2; ++a)
; #pragma unroll
;             for (int b = 0; b < 2; ++b)
; #pragma unroll
;                 for (int m = 0; m < 4; ++m)
; #pragma unroll
;                     for (int n = 0; n < 2; ++n) acc[a][b][m][n] = (f32x4){0.f, 0.f, 0.f, 0.f};
.LBB0_1252:
	s_ashr_i32 s15, s14, 31
	s_lshl_b64 s[16:17], s[14:15], 19
	s_add_u32 s16, s72, s16
	s_addc_u32 s17, s73, s17
	s_and_b64 s[18:19], s[8:9], exec
	s_cselect_b32 s15, s17, s21
	s_cselect_b32 s40, s16, s20
	s_ashr_i32 s13, s12, 31
	s_lshl_b64 s[18:19], s[12:13], 19
	s_add_u32 s18, s2, s18
	s_addc_u32 s19, s3, s19
	s_and_b64 s[24:25], s[8:9], exec
	s_cselect_b32 s13, s19, s23
	s_cselect_b32 s41, s18, s22
	s_add_u32 s20, s20, 0x40080
	s_addc_u32 s21, s21, 0
	s_add_u32 s42, s22, 0x100
	v_mov_b32_e32 v0, 0
	s_addc_u32 s43, s23, 0
	s_mov_b32 s44, -2
	v_mov_b32_e32 v1, v0
	v_mov_b64_e32 v[2:3], v[0:1]
	v_mov_b64_e32 v[4:5], v[0:1]
	v_mov_b64_e32 v[6:7], v[0:1]
	v_mov_b64_e32 v[8:9], v[0:1]
	v_mov_b64_e32 v[10:11], v[0:1]
	v_mov_b64_e32 v[12:13], v[0:1]
	v_mov_b64_e32 v[14:15], v[0:1]
	v_mov_b64_e32 v[16:17], v[0:1]
	v_mov_b64_e32 v[18:19], v[0:1]
	v_mov_b64_e32 v[20:21], v[0:1]
	v_mov_b64_e32 v[22:23], v[0:1]
	v_mov_b64_e32 v[24:25], v[0:1]
	v_mov_b64_e32 v[26:27], v[0:1]
	v_mov_b64_e32 v[28:29], v[0:1]
	v_mov_b64_e32 v[30:31], v[0:1]
	v_mov_b64_e32 v[32:33], v[0:1]
	v_mov_b64_e32 v[34:35], v[0:1]
	v_mov_b64_e32 v[36:37], v[0:1]
	v_mov_b64_e32 v[38:39], v[0:1]
	v_mov_b64_e32 v[40:41], v[0:1]
	v_mov_b64_e32 v[42:43], v[0:1]
	v_mov_b64_e32 v[44:45], v[0:1]
	v_mov_b64_e32 v[46:47], v[0:1]
	v_mov_b64_e32 v[48:49], v[0:1]
	v_mov_b64_e32 v[50:51], v[0:1]
	v_mov_b64_e32 v[52:53], v[0:1]
	v_mov_b64_e32 v[54:55], v[0:1]
	v_mov_b64_e32 v[56:57], v[0:1]
	v_mov_b64_e32 v[58:59], v[0:1]
	v_mov_b64_e32 v[60:61], v[0:1]
	v_mov_b64_e32 v[62:63], v[0:1]
	v_mov_b64_e32 v[64:65], v[0:1]
	v_mov_b64_e32 v[66:67], v[0:1]
	v_mov_b64_e32 v[68:69], v[0:1]
	v_mov_b64_e32 v[70:71], v[0:1]
	v_mov_b64_e32 v[72:73], v[0:1]
	v_mov_b64_e32 v[74:75], v[0:1]
	v_mov_b64_e32 v[76:77], v[0:1]
	v_mov_b64_e32 v[78:79], v[0:1]
	v_mov_b64_e32 v[80:81], v[0:1]
	v_mov_b64_e32 v[82:83], v[0:1]
	v_mov_b64_e32 v[84:85], v[0:1]
	v_mov_b64_e32 v[86:87], v[0:1]
	v_mov_b64_e32 v[88:89], v[0:1]
	v_mov_b64_e32 v[90:91], v[0:1]
	v_mov_b64_e32 v[92:93], v[0:1]
	v_mov_b64_e32 v[94:95], v[0:1]
	v_mov_b64_e32 v[96:97], v[0:1]
	v_mov_b64_e32 v[98:99], v[0:1]
	v_mov_b64_e32 v[100:101], v[0:1]
	v_mov_b64_e32 v[102:103], v[0:1]
	v_mov_b64_e32 v[104:105], v[0:1]
	v_mov_b64_e32 v[106:107], v[0:1]
	v_mov_b64_e32 v[108:109], v[0:1]
	v_mov_b64_e32 v[110:111], v[0:1]
	v_mov_b64_e32 v[112:113], v[0:1]
	v_mov_b64_e32 v[114:115], v[0:1]
	v_mov_b64_e32 v[116:117], v[0:1]
	v_mov_b64_e32 v[118:119], v[0:1]
	v_mov_b64_e32 v[120:121], v[0:1]
	v_mov_b64_e32 v[122:123], v[0:1]
	v_mov_b64_e32 v[124:125], v[0:1]
	v_mov_b64_e32 v[126:127], v[0:1]
	s_waitcnt vmcnt(0)

; template <class Epi, class Sched, bool ALIGN_EPI = false, bool SP2 = false>
; __device__ __forceinline__ void gemm_phase(PG8_LAS unsigned char* lds, const Gemm g, const Sched& S, const Epi& E) {
;     ...
; #pragma unroll
;         for (int a = 0; a < 2; ++a)
; #pragma unroll
;             for (int b = 0; b < 2; ++b)
; #pragma unroll
;                 for (int m = 0; m < 4; ++m)
; #pragma unroll
;                     for (int n = 0; n < 2; ++n) acc[a][b][m][n] = (f32x4){0.f, 0.f, 0.f, 0.f};
.LBB0_1334:
	s_add_u32 s41, s20, 0x100
	v_mov_b32_e32 v0, 0
	s_addc_u32 s42, s21, 0
	s_mov_b32 s43, -2
	s_waitcnt lgkmcnt(0)
	v_mov_b32_e32 v1, v0
	v_mov_b64_e32 v[2:3], v[0:1]
	v_mov_b64_e32 v[4:5], v[0:1]
	v_mov_b64_e32 v[6:7], v[0:1]
	v_mov_b64_e32 v[8:9], v[0:1]
	v_mov_b64_e32 v[10:11], v[0:1]
	v_mov_b64_e32 v[12:13], v[0:1]
	v_mov_b64_e32 v[14:15], v[0:1]
	v_mov_b64_e32 v[16:17], v[0:1]
	v_mov_b64_e32 v[18:19], v[0:1]
	v_mov_b64_e32 v[20:21], v[0:1]
	v_mov_b64_e32 v[22:23], v[0:1]
	v_mov_b64_e32 v[24:25], v[0:1]
	v_mov_b64_e32 v[26:27], v[0:1]
	v_mov_b64_e32 v[28:29], v[0:1]
	v_mov_b64_e32 v[30:31], v[0:1]
	v_mov_b64_e32 v[32:33], v[0:1]
	v_mov_b64_e32 v[34:35], v[0:1]
	v_mov_b64_e32 v[36:37], v[0:1]
	v_mov_b64_e32 v[38:39], v[0:1]
	v_mov_b64_e32 v[40:41], v[0:1]
	v_mov_b64_e32 v[42:43], v[0:1]
	v_mov_b64_e32 v[44:45], v[0:1]
	v_mov_b64_e32 v[46:47], v[0:1]
	v_mov_b64_e32 v[48:49], v[0:1]
	v_mov_b64_e32 v[50:51], v[0:1]
	v_mov_b64_e32 v[52:53], v[0:1]
	v_mov_b64_e32 v[54:55], v[0:1]
	v_mov_b64_e32 v[56:57], v[0:1]
	v_mov_b64_e32 v[58:59], v[0:1]
	v_mov_b64_e32 v[60:61], v[0:1]
	v_mov_b64_e32 v[62:63], v[0:1]
	v_mov_b64_e32 v[64:65], v[0:1]
	v_mov_b64_e32 v[66:67], v[0:1]
	v_mov_b64_e32 v[68:69], v[0:1]
	v_mov_b64_e32 v[70:71], v[0:1]
	v_mov_b64_e32 v[72:73], v[0:1]
	v_mov_b64_e32 v[74:75], v[0:1]
	v_mov_b64_e32 v[76:77], v[0:1]
	v_mov_b64_e32 v[78:79], v[0:1]
	v_mov_b64_e32 v[80:81], v[0:1]
	v_mov_b64_e32 v[82:83], v[0:1]
	v_mov_b64_e32 v[84:85], v[0:1]
	v_mov_b64_e32 v[86:87], v[0:1]
	v_mov_b64_e32 v[88:89], v[0:1]
	v_mov_b64_e32 v[90:91], v[0:1]
	v_mov_b64_e32 v[92:93], v[0:1]
	v_mov_b64_e32 v[94:95], v[0:1]
	v_mov_b64_e32 v[96:97], v[0:1]
	v_mov_b64_e32 v[98:99], v[0:1]
	v_mov_b64_e32 v[100:101], v[0:1]
	v_mov_b64_e32 v[102:103], v[0:1]
	v_mov_b64_e32 v[104:105], v[0:1]
	v_mov_b64_e32 v[106:107], v[0:1]
	v_mov_b64_e32 v[108:109], v[0:1]
	v_mov_b64_e32 v[110:111], v[0:1]
	v_mov_b64_e32 v[112:113], v[0:1]
	v_mov_b64_e32 v[114:115], v[0:1]
	v_mov_b64_e32 v[116:117], v[0:1]
	v_mov_b64_e32 v[118:119], v[0:1]
	v_mov_b64_e32 v[120:121], v[0:1]
	v_mov_b64_e32 v[122:123], v[0:1]
	v_mov_b64_e32 v[124:125], v[0:1]
	v_mov_b64_e32 v[126:127], v[0:1]
	s_waitcnt vmcnt(0)
